# code placement: GEMM K-loop moved by 32 bytes (8 s_nop in the per-unit preheader)
# baseline (speedup 1.0000x reference)
; template <class Epi, class Sched, bool ALIGN_EPI = false, bool SP2 = false>
; __device__ __forceinline__ void gemm_phase(PG8_LAS unsigned char* lds, const Gemm g, const Sched& S, const Epi& E) {
;     ...
; #pragma unroll
;         for (int a = 0; a < 2; ++a)
; #pragma unroll
;             for (int b = 0; b < 2; ++b)
; #pragma unroll
;                 for (int m = 0; m < 4; ++m)
; #pragma unroll
;                     for (int n = 0; n < 2; ++n) acc[a][b][m][n] = (f32x4){0.f, 0.f, 0.f, 0.f};
.LBB0_161:
	s_nop 0
	s_nop 0
	s_nop 0
	s_nop 0
	s_nop 0
	s_nop 0
	s_nop 0
	s_nop 0
	s_add_u32 s25, s10, s21
	v_mov_b32_e32 v0, 0
	s_addc_u32 s26, s11, 0
	s_mov_b64 s[12:13], 0
	v_mov_b32_e32 v1, v0
	v_mov_b32_e32 v2, v0
	v_mov_b32_e32 v3, v0
	v_mov_b32_e32 v8, v0
	v_mov_b32_e32 v9, v0
	v_mov_b32_e32 v10, v0
	v_mov_b32_e32 v11, v0
	v_mov_b32_e32 v16, v0
	v_mov_b32_e32 v17, v0
	v_mov_b32_e32 v18, v0
	v_mov_b32_e32 v19, v0
	v_mov_b32_e32 v24, v0
	v_mov_b32_e32 v25, v0
	v_mov_b32_e32 v26, v0
	v_mov_b32_e32 v27, v0
	v_mov_b32_e32 v32, v0
	v_mov_b32_e32 v33, v0
	v_mov_b32_e32 v34, v0
	v_mov_b32_e32 v35, v0
	v_mov_b32_e32 v40, v0
	v_mov_b32_e32 v41, v0
	v_mov_b32_e32 v42, v0
	v_mov_b32_e32 v43, v0
	v_mov_b32_e32 v48, v0
	v_mov_b32_e32 v49, v0
	v_mov_b32_e32 v50, v0
	v_mov_b32_e32 v51, v0
	v_mov_b32_e32 v56, v0
	v_mov_b32_e32 v57, v0
	v_mov_b32_e32 v58, v0
	v_mov_b32_e32 v59, v0
	v_mov_b32_e32 v4, v0
	v_mov_b32_e32 v5, v0
	v_mov_b32_e32 v6, v0
	v_mov_b32_e32 v7, v0
	v_mov_b32_e32 v12, v0
	v_mov_b32_e32 v13, v0
	v_mov_b32_e32 v14, v0
	v_mov_b32_e32 v15, v0
	v_mov_b32_e32 v20, v0
	v_mov_b32_e32 v21, v0
	v_mov_b32_e32 v22, v0
	v_mov_b32_e32 v23, v0
	v_mov_b32_e32 v28, v0
	v_mov_b32_e32 v29, v0
	v_mov_b32_e32 v30, v0
	v_mov_b32_e32 v31, v0
	v_mov_b32_e32 v36, v0
	v_mov_b32_e32 v37, v0
	v_mov_b32_e32 v38, v0
	v_mov_b32_e32 v39, v0
	v_mov_b32_e32 v44, v0
	v_mov_b32_e32 v45, v0
	v_mov_b32_e32 v46, v0
	v_mov_b32_e32 v47, v0
	v_mov_b32_e32 v52, v0
	v_mov_b32_e32 v53, v0
	v_mov_b32_e32 v54, v0
	v_mov_b32_e32 v55, v0
	v_mov_b32_e32 v60, v0
	v_mov_b32_e32 v61, v0
	v_mov_b32_e32 v62, v0
	v_mov_b32_e32 v63, v0
	v_mov_b32_e32 v64, v0
	v_mov_b32_e32 v65, v0
	v_mov_b32_e32 v66, v0
	v_mov_b32_e32 v67, v0
	v_mov_b32_e32 v72, v0
	v_mov_b32_e32 v73, v0
	v_mov_b32_e32 v74, v0
	v_mov_b32_e32 v75, v0
	v_mov_b32_e32 v80, v0
	v_mov_b32_e32 v81, v0
	v_mov_b32_e32 v82, v0
	v_mov_b32_e32 v83, v0
	v_mov_b32_e32 v88, v0
	v_mov_b32_e32 v89, v0
	v_mov_b32_e32 v90, v0
	v_mov_b32_e32 v91, v0
	v_mov_b32_e32 v96, v0
	v_mov_b32_e32 v97, v0
	v_mov_b32_e32 v98, v0
	v_mov_b32_e32 v99, v0
	v_mov_b32_e32 v104, v0
	v_mov_b32_e32 v105, v0
	v_mov_b32_e32 v106, v0
	v_mov_b32_e32 v107, v0
	s_waitcnt vmcnt(0)
	v_mov_b32_e32 v112, v0
	v_mov_b32_e32 v113, v0
	v_mov_b32_e32 v114, v0
	v_mov_b32_e32 v115, v0
	v_mov_b32_e32 v120, v0
	v_mov_b32_e32 v121, v0
	v_mov_b32_e32 v122, v0
	v_mov_b32_e32 v123, v0
	v_mov_b32_e32 v68, v0
	v_mov_b32_e32 v69, v0
	v_mov_b32_e32 v70, v0
	v_mov_b32_e32 v71, v0
	v_mov_b32_e32 v76, v0
	v_mov_b32_e32 v77, v0
	v_mov_b32_e32 v78, v0
	v_mov_b32_e32 v79, v0
	v_mov_b32_e32 v84, v0
	v_mov_b32_e32 v85, v0
	v_mov_b32_e32 v86, v0
	v_mov_b32_e32 v87, v0
	v_mov_b32_e32 v92, v0
	v_mov_b32_e32 v93, v0
	v_mov_b32_e32 v94, v0
	v_mov_b32_e32 v95, v0
	v_mov_b32_e32 v100, v0
	v_mov_b32_e32 v101, v0
	v_mov_b32_e32 v102, v0
	v_mov_b32_e32 v103, v0
	v_mov_b32_e32 v108, v0
	v_mov_b32_e32 v109, v0
	v_mov_b32_e32 v110, v0
	v_mov_b32_e32 v111, v0
	v_mov_b32_e32 v116, v0
	v_mov_b32_e32 v117, v0
	v_mov_b32_e32 v118, v0
	v_mov_b32_e32 v119, v0
	v_mov_b32_e32 v124, v0
	v_mov_b32_e32 v125, v0
	v_mov_b32_e32 v126, v0
	v_mov_b32_e32 v127, v0
	s_and_b64 vcc, exec, s[86:87]
	s_cbranch_vccnz .Lsp_skip
	s_setprio 1
